# strategy 7 (instruction selection): EpiRes row-sum reductions via v_permlane16/32_swap instead of ds_bpermute round trips
# speedup vs baseline: 1.0049x; 1.0049x over previous
; __device__ __forceinline__ unsigned cvt_pk_bf16(float lo, float hi) { unsigned r; asm volatile("v_cvt_pk_bf16_f32 %0, %1, %2" : "=v"(r) : "v"(lo), "v"(hi)); return r; }
; __device__ __forceinline__ float bf_lo(unsigned w) { return __uint_as_float(w << 16); }
; __device__ __forceinline__ float bf_hi(unsigned w) { return __uint_as_float(w & 0xffff0000u); }
;     __device__ __forceinline__ void operator()(const f32x4 (&acc)[2][2][4][2], const Unit& u, int wr, int wc, int fr, int fq) const {
;     ...
;                 for (int bj = 0; bj < 2; ++bj) xw[m][bj] = *(const u32x4*)(XB + (size_t)(row0 + ai * HALF + m * 16) * D_MODEL + col0 + bj * HALF);
; #pragma unroll
;             for (int m = 0; m < 4; ++m) { const int row = row0 + ai * HALF + m * 16; float ss = 0.f;
; #pragma unroll
;                 for (int bj = 0; bj < 2; ++bj) { const size_t o = (size_t)row * D_MODEL + col0 + bj * HALF; const u32x4 t = xw[m][bj];
;                     f32x4 v0, v1; v0[0] = bf_lo(t.x); v0[1] = bf_hi(t.x); v0[2] = bf_lo(t.y); v0[3] = bf_hi(t.y); v1[0] = bf_lo(t.z); v1[1] = bf_hi(t.z); v1[2] = bf_lo(t.w); v1[3] = bf_hi(t.w);
;                     v0 = v0 + acc[ai][bj][m][0]; v1 = v1 + acc[ai][bj][m][1];
;                     if (aux) { u32x4 w; w.x = cvt_pk_bf16(v0[0], v0[1]); w.y = cvt_pk_bf16(v0[2], v0[3]); w.z = cvt_pk_bf16(v1[0], v1[1]); w.w = cvt_pk_bf16(v1[2], v1[3]);
;                         *(u32x4*)(XB + o) = w;
;                         ss += (v0[0] * v0[0] + v0[1] * v0[1]) + (v0[2] * v0[2] + v0[3] * v0[3]) + (v1[0] * v1[0] + v1[1] * v1[1]) + (v1[2] * v1[2] + v1[3] * v1[3]); }
;                     else { *(f32x4*)(Xout + o) = v0; *(f32x4*)(Xout + o + 4) = v1; } }
;                 if (aux) { ss += __shfl_xor(ss, 16); ss += __shfl_xor(ss, 32); if (fq == 0) red[(ai * HALF + wr * 64 + m * 16 + fr) * 4 + wc] = ss; } } }
.LBB0_556:
	s_lshl_b32 s38, s19, 8
	v_lshl_or_b32 v166, s18, 8, v192
	v_add_u32_e32 v182, s38, v190
	v_ashrrev_i32_e32 v167, 31, v166
	v_lshlrev_b64 v[218:219], 1, v[166:167]
	v_ashrrev_i32_e32 v183, 31, v182
	v_lshl_add_u64 v[180:181], s[56:57], 0, v[218:219]
	v_lshlrev_b64 v[220:221], 12, v[182:183]
	v_lshl_add_u64 v[114:115], v[180:181], 0, v[220:221]
	global_load_dwordx4 v[196:199], v[114:115], off
	global_load_dwordx4 v[200:203], v[114:115], off offset:256
	v_or_b32_e32 v114, 16, v182
	v_ashrrev_i32_e32 v115, 31, v114
	v_lshlrev_b64 v[188:189], 12, v[114:115]
	v_lshl_add_u64 v[114:115], v[180:181], 0, v[188:189]
	global_load_dwordx4 v[150:153], v[114:115], off
	global_load_dwordx4 v[146:149], v[114:115], off offset:256
	v_or_b32_e32 v114, 32, v182
	v_ashrrev_i32_e32 v115, 31, v114
	v_lshlrev_b64 v[186:187], 12, v[114:115]
	v_lshl_add_u64 v[114:115], v[180:181], 0, v[186:187]
	global_load_dwordx4 v[134:137], v[114:115], off
	global_load_dwordx4 v[122:125], v[114:115], off offset:256
	v_or_b32_e32 v114, 48, v182
	v_ashrrev_i32_e32 v115, 31, v114
	v_lshlrev_b64 v[184:185], 12, v[114:115]
	v_lshl_add_u64 v[114:115], v[180:181], 0, v[184:185]
	global_load_dwordx4 v[118:121], v[114:115], off
	s_nop 0
	global_load_dwordx4 v[114:117], v[114:115], off offset:256
	v_lshl_add_u64 v[220:221], s[56:57], 0, v[220:221]
	v_lshl_add_u64 v[218:219], v[220:221], 0, v[218:219]
	s_waitcnt vmcnt(0)
	v_lshlrev_b32_e32 v222, 16, v196
	v_and_b32_e32 v223, 0xffff0000, v196
	v_lshlrev_b32_e32 v196, 16, v197
	v_and_b32_e32 v197, 0xffff0000, v197
	v_lshlrev_b32_e32 v224, 16, v198
	v_and_b32_e32 v225, 0xffff0000, v198
	v_lshlrev_b32_e32 v198, 16, v199
	v_and_b32_e32 v199, 0xffff0000, v199
	v_pk_add_f32 v[144:145], v[144:145], v[196:197]
	v_pk_add_f32 v[142:143], v[142:143], v[222:223]
	v_pk_add_f32 v[196:197], v[140:141], v[198:199]
	v_pk_add_f32 v[198:199], v[138:139], v[224:225]
	v_cvt_pk_bf16_f32 v138, v142, v143
	v_cvt_pk_bf16_f32 v139, v144, v145
	s_nop 0
	v_cvt_pk_bf16_f32 v140, v198, v199
	v_cvt_pk_bf16_f32 v141, v196, v197
	global_store_dwordx4 v[218:219], v[138:141], off
	s_nop 1
	v_mul_f32_e32 v138, v143, v143
	v_mul_f32_e32 v139, v145, v145
	v_fmac_f32_e32 v138, v142, v142
	v_fmac_f32_e32 v139, v144, v144
	v_add_f32_e32 v138, v138, v139
	v_mul_f32_e32 v139, v199, v199
	v_fmac_f32_e32 v139, v198, v198
	v_add_f32_e32 v138, v139, v138
	v_mul_f32_e32 v139, v197, v197
	v_fmac_f32_e32 v139, v196, v196
	v_add_f32_e32 v196, v139, v138
	v_lshlrev_b32_e32 v138, 16, v200
	v_and_b32_e32 v139, 0xffff0000, v200
	v_lshlrev_b32_e32 v140, 16, v201
	v_and_b32_e32 v141, 0xffff0000, v201
	v_lshlrev_b32_e32 v142, 16, v202
	v_and_b32_e32 v143, 0xffff0000, v202
	v_lshlrev_b32_e32 v144, 16, v203
	v_and_b32_e32 v145, 0xffff0000, v203
	v_pk_add_f32 v[132:133], v[132:133], v[140:141]
	v_pk_add_f32 v[130:131], v[130:131], v[138:139]
	v_pk_add_f32 v[140:141], v[126:127], v[142:143]
	v_cvt_pk_bf16_f32 v126, v130, v131
	v_cvt_pk_bf16_f32 v127, v132, v133
	v_pk_add_f32 v[138:139], v[128:129], v[144:145]
	v_cvt_pk_bf16_f32 v128, v140, v141
	s_nop 0
	v_cvt_pk_bf16_f32 v129, v138, v139
	global_store_dwordx4 v[218:219], v[126:129], off offset:256
	s_nop 1
	v_mul_f32_e32 v126, v131, v131
	v_mul_f32_e32 v127, v133, v133
	v_fmac_f32_e32 v126, v130, v130
	v_fmac_f32_e32 v127, v132, v132
	v_add_f32_e32 v126, v126, v127
	v_mul_f32_e32 v127, v141, v141
	v_fmac_f32_e32 v127, v140, v140
	v_add_f32_e32 v126, v127, v126
	v_mul_f32_e32 v127, v139, v139
	v_fmac_f32_e32 v127, v138, v138
	v_add_f32_e32 v126, v127, v126
	v_and_b32_e32 v128, 64, v211
	v_add_f32_e32 v127, v196, v126
	v_xor_b32_e32 v126, 16, v211
	v_add_u32_e32 v129, 64, v128
	v_cmp_lt_i32_e32 vcc, v126, v129
	s_nop 1
	v_cndmask_b32_e32 v126, v211, v126, vcc
	v_lshlrev_b32_e32 v126, 2, v126
	v_mov_b32_e32 v128, v127
	s_nop 1
	v_permlane16_swap_b32_e32 v127, v128
	s_waitcnt lgkmcnt(0)
	v_add_f32_e32 v128, v127, v128
	v_xor_b32_e32 v127, 32, v211
	v_cmp_lt_i32_e32 vcc, v127, v129
	s_nop 1
	v_cndmask_b32_e32 v127, v211, v127, vcc
	v_lshlrev_b32_e32 v127, 2, v127
	v_mov_b32_e32 v129, v128
	s_nop 1
	v_permlane32_swap_b32_e32 v128, v129
	s_and_saveexec_b64 s[16:17], s[40:41]
	s_cbranch_execz .LBB0_558
	s_waitcnt lgkmcnt(0)
	v_add_f32_e32 v128, v128, v129
	ds_write_b32 v193, v128
.LBB0_558:
	s_or_b64 exec, exec, s[16:17]
	v_lshlrev_b32_e32 v128, 16, v150
	s_waitcnt lgkmcnt(0)
	v_and_b32_e32 v129, 0xffff0000, v150
	v_lshlrev_b32_e32 v130, 16, v151
	v_and_b32_e32 v131, 0xffff0000, v151
	v_lshlrev_b32_e32 v132, 16, v152
	v_and_b32_e32 v133, 0xffff0000, v152
	v_pk_add_f32 v[110:111], v[110:111], v[128:129]
	v_pk_add_f32 v[112:113], v[112:113], v[130:131]
	v_pk_add_f32 v[130:131], v[106:107], v[132:133]
	v_cvt_pk_bf16_f32 v106, v110, v111
	v_mul_f32_e32 v111, v111, v111
	v_fmac_f32_e32 v111, v110, v110
	v_mul_f32_e32 v110, v113, v113
	v_fmac_f32_e32 v110, v112, v112
	v_lshlrev_b32_e32 v138, 16, v153
	v_and_b32_e32 v139, 0xffff0000, v153
	v_add_f32_e32 v110, v111, v110
	v_mul_f32_e32 v111, v131, v131
	v_pk_add_f32 v[128:129], v[108:109], v[138:139]
	v_fmac_f32_e32 v111, v130, v130
	v_add_f32_e32 v110, v111, v110
	v_mul_f32_e32 v111, v129, v129
	v_fmac_f32_e32 v111, v128, v128
	v_cvt_pk_bf16_f32 v107, v112, v113
	v_add_f32_e32 v132, v111, v110
	v_lshlrev_b32_e32 v110, 16, v146
	v_and_b32_e32 v111, 0xffff0000, v146
	v_lshlrev_b32_e32 v112, 16, v147
	v_and_b32_e32 v113, 0xffff0000, v147
	v_cvt_pk_bf16_f32 v108, v130, v131
	v_cvt_pk_bf16_f32 v109, v128, v129
	v_lshlrev_b32_e32 v128, 16, v148
	v_and_b32_e32 v129, 0xffff0000, v148
	v_pk_add_f32 v[104:105], v[104:105], v[112:113]
	v_pk_add_f32 v[102:103], v[102:103], v[110:111]
	v_pk_add_f32 v[112:113], v[98:99], v[128:129]
	v_mul_f32_e32 v98, v103, v103
	v_mul_f32_e32 v99, v105, v105
	v_fmac_f32_e32 v98, v102, v102
	v_fmac_f32_e32 v99, v104, v104
	v_lshlrev_b32_e32 v130, 16, v149
	v_and_b32_e32 v131, 0xffff0000, v149
	v_add_f32_e32 v98, v98, v99
	v_mul_f32_e32 v99, v113, v113
	v_pk_add_f32 v[110:111], v[100:101], v[130:131]
	v_fmac_f32_e32 v99, v112, v112
	v_add_f32_e32 v98, v99, v98
	v_mul_f32_e32 v99, v111, v111
	v_fmac_f32_e32 v99, v110, v110
	v_add_f32_e32 v98, v99, v98
	v_add_f32_e32 v101, v132, v98
	v_mov_b32_e32 v130, v101
	s_nop 1
	v_permlane16_swap_b32_e32 v101, v130
	v_lshl_add_u64 v[98:99], s[56:57], 0, v[188:189]
	v_lshl_add_u64 v[128:129], v[166:167], 1, v[98:99]
	global_store_dwordx4 v[128:129], v[106:109], off
	v_cvt_pk_bf16_f32 v100, v102, v103
	s_waitcnt lgkmcnt(0)
	v_add_f32_e32 v98, v101, v130
	v_mov_b32_e32 v99, v98
	s_nop 1
	v_permlane32_swap_b32_e32 v98, v99
	v_cvt_pk_bf16_f32 v101, v104, v105
	v_cvt_pk_bf16_f32 v102, v112, v113
	v_cvt_pk_bf16_f32 v103, v110, v111
	global_store_dwordx4 v[128:129], v[100:103], off offset:256
	s_and_saveexec_b64 s[16:17], s[40:41]
	s_cbranch_execz .LBB0_560
	s_waitcnt lgkmcnt(0)
	v_add_f32_e32 v98, v98, v99
	ds_write_b32 v193, v98 offset:256
; __device__ __forceinline__ unsigned cvt_pk_bf16(float lo, float hi) { unsigned r; asm volatile("v_cvt_pk_bf16_f32 %0, %1, %2" : "=v"(r) : "v"(lo), "v"(hi)); return r; }
; __device__ __forceinline__ float bf_lo(unsigned w) { return __uint_as_float(w << 16); }
; __device__ __forceinline__ float bf_hi(unsigned w) { return __uint_as_float(w & 0xffff0000u); }
;     __device__ __forceinline__ void operator()(const f32x4 (&acc)[2][2][4][2], const Unit& u, int wr, int wc, int fr, int fq) const {
;     ...
;                 for (int bj = 0; bj < 2; ++bj) xw[m][bj] = *(const u32x4*)(XB + (size_t)(row0 + ai * HALF + m * 16) * D_MODEL + col0 + bj * HALF);
; #pragma unroll
;             for (int m = 0; m < 4; ++m) { const int row = row0 + ai * HALF + m * 16; float ss = 0.f;
; #pragma unroll
;                 for (int bj = 0; bj < 2; ++bj) { const size_t o = (size_t)row * D_MODEL + col0 + bj * HALF; const u32x4 t = xw[m][bj];
;                     f32x4 v0, v1; v0[0] = bf_lo(t.x); v0[1] = bf_hi(t.x); v0[2] = bf_lo(t.y); v0[3] = bf_hi(t.y); v1[0] = bf_lo(t.z); v1[1] = bf_hi(t.z); v1[2] = bf_lo(t.w); v1[3] = bf_hi(t.w);
;                     v0 = v0 + acc[ai][bj][m][0]; v1 = v1 + acc[ai][bj][m][1];
;                     if (aux) { u32x4 w; w.x = cvt_pk_bf16(v0[0], v0[1]); w.y = cvt_pk_bf16(v0[2], v0[3]); w.z = cvt_pk_bf16(v1[0], v1[1]); w.w = cvt_pk_bf16(v1[2], v1[3]);
;                         *(u32x4*)(XB + o) = w;
;                         ss += (v0[0] * v0[0] + v0[1] * v0[1]) + (v0[2] * v0[2] + v0[3] * v0[3]) + (v1[0] * v1[0] + v1[1] * v1[1]) + (v1[2] * v1[2] + v1[3] * v1[3]); }
;                     else { *(f32x4*)(Xout + o) = v0; *(f32x4*)(Xout + o + 4) = v1; } }
;                 if (aux) { ss += __shfl_xor(ss, 16); ss += __shfl_xor(ss, 32); if (fq == 0) red[(ai * HALF + wr * 64 + m * 16 + fr) * 4 + wc] = ss; } } }
.LBB0_560:
	s_or_b64 exec, exec, s[16:17]
	v_lshlrev_b32_e32 v98, 16, v134
	s_waitcnt lgkmcnt(0)
	v_and_b32_e32 v99, 0xffff0000, v134
	v_lshlrev_b32_e32 v100, 16, v135
	v_and_b32_e32 v101, 0xffff0000, v135
	v_lshlrev_b32_e32 v102, 16, v136
	v_and_b32_e32 v103, 0xffff0000, v136
	v_pk_add_f32 v[94:95], v[94:95], v[98:99]
	v_pk_add_f32 v[96:97], v[96:97], v[100:101]
	v_pk_add_f32 v[100:101], v[90:91], v[102:103]
	v_cvt_pk_bf16_f32 v90, v94, v95
	v_mul_f32_e32 v95, v95, v95
	v_fmac_f32_e32 v95, v94, v94
	v_mul_f32_e32 v94, v97, v97
	v_fmac_f32_e32 v94, v96, v96
	v_lshlrev_b32_e32 v104, 16, v137
	v_and_b32_e32 v105, 0xffff0000, v137
	v_add_f32_e32 v94, v95, v94
	v_mul_f32_e32 v95, v101, v101
	v_pk_add_f32 v[98:99], v[92:93], v[104:105]
	v_fmac_f32_e32 v95, v100, v100
	v_add_f32_e32 v94, v95, v94
	v_mul_f32_e32 v95, v99, v99
	v_fmac_f32_e32 v95, v98, v98
	v_cvt_pk_bf16_f32 v91, v96, v97
	v_add_f32_e32 v102, v95, v94
	v_lshlrev_b32_e32 v94, 16, v122
	v_and_b32_e32 v95, 0xffff0000, v122
	v_lshlrev_b32_e32 v96, 16, v123
	v_and_b32_e32 v97, 0xffff0000, v123
	v_cvt_pk_bf16_f32 v92, v100, v101
	v_cvt_pk_bf16_f32 v93, v98, v99
	v_lshlrev_b32_e32 v98, 16, v124
	v_and_b32_e32 v99, 0xffff0000, v124
	v_pk_add_f32 v[88:89], v[88:89], v[96:97]
	v_pk_add_f32 v[86:87], v[86:87], v[94:95]
	v_pk_add_f32 v[96:97], v[82:83], v[98:99]
	v_mul_f32_e32 v82, v87, v87
	v_mul_f32_e32 v83, v89, v89
	v_fmac_f32_e32 v82, v86, v86
	v_fmac_f32_e32 v83, v88, v88
	v_lshlrev_b32_e32 v100, 16, v125
	v_and_b32_e32 v101, 0xffff0000, v125
	v_add_f32_e32 v82, v82, v83
	v_mul_f32_e32 v83, v97, v97
	v_pk_add_f32 v[94:95], v[84:85], v[100:101]
	v_fmac_f32_e32 v83, v96, v96
	v_add_f32_e32 v82, v83, v82
	v_mul_f32_e32 v83, v95, v95
	v_fmac_f32_e32 v83, v94, v94
	v_add_f32_e32 v82, v83, v82
	v_add_f32_e32 v85, v102, v82
	v_mov_b32_e32 v100, v85
	s_nop 1
	v_permlane16_swap_b32_e32 v85, v100
	v_lshl_add_u64 v[82:83], s[56:57], 0, v[186:187]
	v_lshl_add_u64 v[98:99], v[166:167], 1, v[82:83]
	global_store_dwordx4 v[98:99], v[90:93], off
	v_cvt_pk_bf16_f32 v84, v86, v87
	s_waitcnt lgkmcnt(0)
	v_add_f32_e32 v82, v85, v100
	v_mov_b32_e32 v83, v82
	s_nop 1
	v_permlane32_swap_b32_e32 v82, v83
	v_cvt_pk_bf16_f32 v85, v88, v89
	v_cvt_pk_bf16_f32 v86, v96, v97
	v_cvt_pk_bf16_f32 v87, v94, v95
	global_store_dwordx4 v[98:99], v[84:87], off offset:256
	s_and_saveexec_b64 s[16:17], s[40:41]
	s_cbranch_execz .LBB0_562
	s_waitcnt lgkmcnt(0)
	v_add_f32_e32 v82, v82, v83
	ds_write_b32 v193, v82 offset:512
.LBB0_562:
	s_or_b64 exec, exec, s[16:17]
	v_lshlrev_b32_e32 v82, 16, v118
	s_waitcnt lgkmcnt(0)
	v_and_b32_e32 v83, 0xffff0000, v118
	v_lshlrev_b32_e32 v84, 16, v119
	v_and_b32_e32 v85, 0xffff0000, v119
	v_lshlrev_b32_e32 v86, 16, v120
	v_and_b32_e32 v87, 0xffff0000, v120
	v_pk_add_f32 v[78:79], v[78:79], v[82:83]
	v_pk_add_f32 v[80:81], v[80:81], v[84:85]
	v_pk_add_f32 v[84:85], v[74:75], v[86:87]
	v_cvt_pk_bf16_f32 v74, v78, v79
	v_mul_f32_e32 v79, v79, v79
	v_fmac_f32_e32 v79, v78, v78
	v_mul_f32_e32 v78, v81, v81
	v_fmac_f32_e32 v78, v80, v80
	v_lshlrev_b32_e32 v88, 16, v121
	v_and_b32_e32 v89, 0xffff0000, v121
	v_add_f32_e32 v78, v79, v78
	v_mul_f32_e32 v79, v85, v85
	v_pk_add_f32 v[82:83], v[76:77], v[88:89]
	v_fmac_f32_e32 v79, v84, v84
	v_add_f32_e32 v78, v79, v78
	v_mul_f32_e32 v79, v83, v83
	v_fmac_f32_e32 v79, v82, v82
	v_cvt_pk_bf16_f32 v75, v80, v81
	v_add_f32_e32 v86, v79, v78
	v_lshlrev_b32_e32 v78, 16, v114
	v_and_b32_e32 v79, 0xffff0000, v114
	v_lshlrev_b32_e32 v80, 16, v115
	v_and_b32_e32 v81, 0xffff0000, v115
	v_cvt_pk_bf16_f32 v76, v84, v85
	v_cvt_pk_bf16_f32 v77, v82, v83
	v_lshlrev_b32_e32 v82, 16, v116
	v_and_b32_e32 v83, 0xffff0000, v116
	v_pk_add_f32 v[72:73], v[72:73], v[80:81]
	v_pk_add_f32 v[70:71], v[70:71], v[78:79]
	v_pk_add_f32 v[80:81], v[66:67], v[82:83]
	v_mul_f32_e32 v66, v71, v71
	v_mul_f32_e32 v67, v73, v73
	v_fmac_f32_e32 v66, v70, v70
	v_fmac_f32_e32 v67, v72, v72
	v_lshlrev_b32_e32 v84, 16, v117
	v_and_b32_e32 v85, 0xffff0000, v117
	v_add_f32_e32 v66, v66, v67
	v_mul_f32_e32 v67, v81, v81
	v_pk_add_f32 v[78:79], v[68:69], v[84:85]
	v_fmac_f32_e32 v67, v80, v80
	v_add_f32_e32 v66, v67, v66
	v_mul_f32_e32 v67, v79, v79
	v_fmac_f32_e32 v67, v78, v78
	v_add_f32_e32 v66, v67, v66
	v_add_f32_e32 v69, v86, v66
	v_mov_b32_e32 v84, v69
	s_nop 1
	v_permlane16_swap_b32_e32 v69, v84
	v_lshl_add_u64 v[66:67], s[56:57], 0, v[184:185]
	v_lshl_add_u64 v[82:83], v[166:167], 1, v[66:67]
	global_store_dwordx4 v[82:83], v[74:77], off
	v_cvt_pk_bf16_f32 v68, v70, v71
	s_waitcnt lgkmcnt(0)
	v_add_f32_e32 v66, v69, v84
	v_mov_b32_e32 v67, v66
	s_nop 1
	v_permlane32_swap_b32_e32 v66, v67
	v_cvt_pk_bf16_f32 v69, v72, v73
	v_cvt_pk_bf16_f32 v70, v80, v81
	v_cvt_pk_bf16_f32 v71, v78, v79
	global_store_dwordx4 v[82:83], v[68:71], off offset:256
	s_and_saveexec_b64 s[16:17], s[40:41]
	s_cbranch_execz .LBB0_564
	s_waitcnt lgkmcnt(0)
	v_add_f32_e32 v66, v66, v67
	ds_write_b32 v193, v66 offset:768
; __device__ __forceinline__ unsigned cvt_pk_bf16(float lo, float hi) { unsigned r; asm volatile("v_cvt_pk_bf16_f32 %0, %1, %2" : "=v"(r) : "v"(lo), "v"(hi)); return r; }
; __device__ __forceinline__ float bf_lo(unsigned w) { return __uint_as_float(w << 16); }
; __device__ __forceinline__ float bf_hi(unsigned w) { return __uint_as_float(w & 0xffff0000u); }
;     __device__ __forceinline__ void operator()(const f32x4 (&acc)[2][2][4][2], const Unit& u, int wr, int wc, int fr, int fq) const {
;     ...
;                 for (int bj = 0; bj < 2; ++bj) xw[m][bj] = *(const u32x4*)(XB + (size_t)(row0 + ai * HALF + m * 16) * D_MODEL + col0 + bj * HALF);
; #pragma unroll
;             for (int m = 0; m < 4; ++m) { const int row = row0 + ai * HALF + m * 16; float ss = 0.f;
; #pragma unroll
;                 for (int bj = 0; bj < 2; ++bj) { const size_t o = (size_t)row * D_MODEL + col0 + bj * HALF; const u32x4 t = xw[m][bj];
;                     f32x4 v0, v1; v0[0] = bf_lo(t.x); v0[1] = bf_hi(t.x); v0[2] = bf_lo(t.y); v0[3] = bf_hi(t.y); v1[0] = bf_lo(t.z); v1[1] = bf_hi(t.z); v1[2] = bf_lo(t.w); v1[3] = bf_hi(t.w);
;                     v0 = v0 + acc[ai][bj][m][0]; v1 = v1 + acc[ai][bj][m][1];
;                     if (aux) { u32x4 w; w.x = cvt_pk_bf16(v0[0], v0[1]); w.y = cvt_pk_bf16(v0[2], v0[3]); w.z = cvt_pk_bf16(v1[0], v1[1]); w.w = cvt_pk_bf16(v1[2], v1[3]);
;                         *(u32x4*)(XB + o) = w;
;                         ss += (v0[0] * v0[0] + v0[1] * v0[1]) + (v0[2] * v0[2] + v0[3] * v0[3]) + (v1[0] * v1[0] + v1[1] * v1[1]) + (v1[2] * v1[2] + v1[3] * v1[3]); }
;                     else { *(f32x4*)(Xout + o) = v0; *(f32x4*)(Xout + o + 4) = v1; } }
;                 if (aux) { ss += __shfl_xor(ss, 16); ss += __shfl_xor(ss, 32); if (fq == 0) red[(ai * HALF + wr * 64 + m * 16 + fr) * 4 + wc] = ss; } } }
.LBB0_564:
	s_or_b64 exec, exec, s[16:17]
	s_waitcnt lgkmcnt(0)
	v_lshlrev_b64 v[66:67], 12, v[182:183]
	s_mov_b64 s[16:17], 0x80000
	v_lshl_add_u64 v[104:105], v[66:67], 0, s[16:17]
	v_lshl_add_u64 v[68:69], v[180:181], 0, v[104:105]
	global_load_dwordx4 v[96:99], v[68:69], off
	global_load_dwordx4 v[100:103], v[68:69], off offset:256
	s_mov_b64 s[16:17], 0x90000
	v_lshl_add_u64 v[94:95], v[66:67], 0, s[16:17]
	s_mov_b64 s[16:17], 0xa0000
	v_lshl_add_u64 v[92:93], v[66:67], 0, s[16:17]
	s_mov_b64 s[16:17], 0xb0000
	v_lshl_add_u64 v[68:69], v[180:181], 0, v[94:95]
	v_lshl_add_u64 v[90:91], v[66:67], 0, s[16:17]
	global_load_dwordx4 v[86:89], v[68:69], off
	global_load_dwordx4 v[82:85], v[68:69], off offset:256
	v_lshl_add_u64 v[68:69], v[180:181], 0, v[92:93]
	v_lshl_add_u64 v[66:67], v[180:181], 0, v[90:91]
	global_load_dwordx4 v[78:81], v[68:69], off
	global_load_dwordx4 v[74:77], v[68:69], off offset:256
	global_load_dwordx4 v[70:73], v[66:67], off
	s_nop 0
	global_load_dwordx4 v[66:69], v[66:67], off offset:256
	v_lshl_add_u64 v[104:105], s[56:57], 0, v[104:105]
	v_lshl_add_u64 v[104:105], v[166:167], 1, v[104:105]
	s_waitcnt vmcnt(7)
	v_lshlrev_b32_e32 v106, 16, v96
	v_and_b32_e32 v107, 0xffff0000, v96
	v_lshlrev_b32_e32 v96, 16, v97
	v_and_b32_e32 v97, 0xffff0000, v97
	v_lshlrev_b32_e32 v108, 16, v98
	v_and_b32_e32 v109, 0xffff0000, v98
	v_lshlrev_b32_e32 v98, 16, v99
	v_and_b32_e32 v99, 0xffff0000, v99
	v_pk_add_f32 v[64:65], v[64:65], v[96:97]
	v_pk_add_f32 v[62:63], v[62:63], v[106:107]
	v_pk_add_f32 v[96:97], v[60:61], v[98:99]
	v_pk_add_f32 v[98:99], v[58:59], v[108:109]
	v_cvt_pk_bf16_f32 v58, v62, v63
	v_cvt_pk_bf16_f32 v59, v64, v65
	s_nop 0
	v_cvt_pk_bf16_f32 v60, v98, v99
	v_cvt_pk_bf16_f32 v61, v96, v97
	global_store_dwordx4 v[104:105], v[58:61], off
	s_nop 1
	v_mul_f32_e32 v58, v63, v63
	v_mul_f32_e32 v59, v65, v65
	v_fmac_f32_e32 v58, v62, v62
	v_fmac_f32_e32 v59, v64, v64
	v_add_f32_e32 v58, v58, v59
	v_mul_f32_e32 v59, v99, v99
	v_fmac_f32_e32 v59, v98, v98
	v_add_f32_e32 v58, v59, v58
	v_mul_f32_e32 v59, v97, v97
	v_fmac_f32_e32 v59, v96, v96
	v_add_f32_e32 v96, v59, v58
	s_waitcnt vmcnt(7)
	v_lshlrev_b32_e32 v58, 16, v100
	v_and_b32_e32 v59, 0xffff0000, v100
	v_lshlrev_b32_e32 v60, 16, v101
	v_and_b32_e32 v61, 0xffff0000, v101
	v_lshlrev_b32_e32 v62, 16, v102
	v_and_b32_e32 v63, 0xffff0000, v102
	v_lshlrev_b32_e32 v64, 16, v103
	v_and_b32_e32 v65, 0xffff0000, v103
	v_pk_add_f32 v[56:57], v[56:57], v[60:61]
	v_pk_add_f32 v[54:55], v[54:55], v[58:59]
	v_pk_add_f32 v[60:61], v[50:51], v[62:63]
	v_cvt_pk_bf16_f32 v50, v54, v55
	v_cvt_pk_bf16_f32 v51, v56, v57
	v_pk_add_f32 v[58:59], v[52:53], v[64:65]
	v_cvt_pk_bf16_f32 v52, v60, v61
	s_nop 0
	v_cvt_pk_bf16_f32 v53, v58, v59
	global_store_dwordx4 v[104:105], v[50:53], off offset:256
	s_nop 1
	v_mul_f32_e32 v50, v55, v55
	v_mul_f32_e32 v51, v57, v57
	v_fmac_f32_e32 v50, v54, v54
	v_fmac_f32_e32 v51, v56, v56
	v_add_f32_e32 v50, v50, v51
	v_mul_f32_e32 v51, v61, v61
	v_fmac_f32_e32 v51, v60, v60
	v_add_f32_e32 v50, v51, v50
	v_mul_f32_e32 v51, v59, v59
	v_fmac_f32_e32 v51, v58, v58
	v_add_f32_e32 v50, v51, v50
	v_add_f32_e32 v50, v96, v50
	v_mov_b32_e32 v51, v50
	s_nop 1
	v_permlane16_swap_b32_e32 v50, v51
	s_waitcnt lgkmcnt(0)
	v_add_f32_e32 v50, v50, v51
	v_mov_b32_e32 v51, v50
	s_nop 1
	v_permlane32_swap_b32_e32 v50, v51
	s_and_saveexec_b64 s[16:17], s[40:41]
	s_cbranch_execz .LBB0_566
	s_waitcnt lgkmcnt(0)
	v_add_f32_e32 v50, v50, v51
	ds_write_b32 v193, v50 offset:2048
.LBB0_566:
	s_or_b64 exec, exec, s[16:17]
	s_waitcnt vmcnt(7)
	v_lshlrev_b32_e32 v50, 16, v86
	s_waitcnt lgkmcnt(0)
	v_and_b32_e32 v51, 0xffff0000, v86
	v_lshlrev_b32_e32 v52, 16, v87
	v_and_b32_e32 v53, 0xffff0000, v87
	v_lshlrev_b32_e32 v54, 16, v88
	v_and_b32_e32 v55, 0xffff0000, v88
	v_pk_add_f32 v[46:47], v[46:47], v[50:51]
	v_pk_add_f32 v[48:49], v[48:49], v[52:53]
	v_pk_add_f32 v[52:53], v[42:43], v[54:55]
	v_cvt_pk_bf16_f32 v42, v46, v47
	v_mul_f32_e32 v47, v47, v47
	v_fmac_f32_e32 v47, v46, v46
	v_mul_f32_e32 v46, v49, v49
	v_fmac_f32_e32 v46, v48, v48
	v_lshlrev_b32_e32 v56, 16, v89
	v_and_b32_e32 v57, 0xffff0000, v89
	v_add_f32_e32 v46, v47, v46
	v_mul_f32_e32 v47, v53, v53
	v_pk_add_f32 v[50:51], v[44:45], v[56:57]
	v_fmac_f32_e32 v47, v52, v52
	v_add_f32_e32 v46, v47, v46
	v_mul_f32_e32 v47, v51, v51
	v_fmac_f32_e32 v47, v50, v50
	v_cvt_pk_bf16_f32 v43, v48, v49
	v_add_f32_e32 v54, v47, v46
	s_waitcnt vmcnt(6)
	v_lshlrev_b32_e32 v46, 16, v82
	v_and_b32_e32 v47, 0xffff0000, v82
	v_lshlrev_b32_e32 v48, 16, v83
	v_and_b32_e32 v49, 0xffff0000, v83
	v_cvt_pk_bf16_f32 v44, v52, v53
	v_cvt_pk_bf16_f32 v45, v50, v51
	v_lshlrev_b32_e32 v50, 16, v84
	v_and_b32_e32 v51, 0xffff0000, v84
	v_pk_add_f32 v[40:41], v[40:41], v[48:49]
	v_pk_add_f32 v[38:39], v[38:39], v[46:47]
	v_pk_add_f32 v[48:49], v[34:35], v[50:51]
	v_mul_f32_e32 v34, v39, v39
	v_mul_f32_e32 v35, v41, v41
	v_fmac_f32_e32 v34, v38, v38
	v_fmac_f32_e32 v35, v40, v40
	v_lshlrev_b32_e32 v52, 16, v85
	v_and_b32_e32 v53, 0xffff0000, v85
	v_add_f32_e32 v34, v34, v35
	v_mul_f32_e32 v35, v49, v49
	v_pk_add_f32 v[46:47], v[36:37], v[52:53]
	v_fmac_f32_e32 v35, v48, v48
	v_add_f32_e32 v34, v35, v34
	v_mul_f32_e32 v35, v47, v47
	v_fmac_f32_e32 v35, v46, v46
	v_add_f32_e32 v34, v35, v34
	v_add_f32_e32 v37, v54, v34
	v_mov_b32_e32 v52, v37
	s_nop 1
	v_permlane16_swap_b32_e32 v37, v52
	v_lshl_add_u64 v[34:35], s[56:57], 0, v[94:95]
	v_lshl_add_u64 v[50:51], v[166:167], 1, v[34:35]
	global_store_dwordx4 v[50:51], v[42:45], off
	v_cvt_pk_bf16_f32 v36, v38, v39
	s_waitcnt lgkmcnt(0)
	v_add_f32_e32 v34, v37, v52
	v_mov_b32_e32 v35, v34
	s_nop 1
	v_permlane32_swap_b32_e32 v34, v35
	v_cvt_pk_bf16_f32 v37, v40, v41
	v_cvt_pk_bf16_f32 v38, v48, v49
	v_cvt_pk_bf16_f32 v39, v46, v47
	global_store_dwordx4 v[50:51], v[36:39], off offset:256
	s_and_saveexec_b64 s[16:17], s[40:41]
	s_cbranch_execz .LBB0_568
	s_waitcnt lgkmcnt(0)
	v_add_f32_e32 v34, v34, v35
	ds_write_b32 v193, v34 offset:2304
; __device__ __forceinline__ unsigned cvt_pk_bf16(float lo, float hi) { unsigned r; asm volatile("v_cvt_pk_bf16_f32 %0, %1, %2" : "=v"(r) : "v"(lo), "v"(hi)); return r; }
; __device__ __forceinline__ float bf_lo(unsigned w) { return __uint_as_float(w << 16); }
; __device__ __forceinline__ float bf_hi(unsigned w) { return __uint_as_float(w & 0xffff0000u); }
;     __device__ __forceinline__ void operator()(const f32x4 (&acc)[2][2][4][2], const Unit& u, int wr, int wc, int fr, int fq) const {
;     ...
;                 for (int bj = 0; bj < 2; ++bj) xw[m][bj] = *(const u32x4*)(XB + (size_t)(row0 + ai * HALF + m * 16) * D_MODEL + col0 + bj * HALF);
; #pragma unroll
;             for (int m = 0; m < 4; ++m) { const int row = row0 + ai * HALF + m * 16; float ss = 0.f;
; #pragma unroll
;                 for (int bj = 0; bj < 2; ++bj) { const size_t o = (size_t)row * D_MODEL + col0 + bj * HALF; const u32x4 t = xw[m][bj];
;                     f32x4 v0, v1; v0[0] = bf_lo(t.x); v0[1] = bf_hi(t.x); v0[2] = bf_lo(t.y); v0[3] = bf_hi(t.y); v1[0] = bf_lo(t.z); v1[1] = bf_hi(t.z); v1[2] = bf_lo(t.w); v1[3] = bf_hi(t.w);
;                     v0 = v0 + acc[ai][bj][m][0]; v1 = v1 + acc[ai][bj][m][1];
;                     if (aux) { u32x4 w; w.x = cvt_pk_bf16(v0[0], v0[1]); w.y = cvt_pk_bf16(v0[2], v0[3]); w.z = cvt_pk_bf16(v1[0], v1[1]); w.w = cvt_pk_bf16(v1[2], v1[3]);
;                         *(u32x4*)(XB + o) = w;
;                         ss += (v0[0] * v0[0] + v0[1] * v0[1]) + (v0[2] * v0[2] + v0[3] * v0[3]) + (v1[0] * v1[0] + v1[1] * v1[1]) + (v1[2] * v1[2] + v1[3] * v1[3]); }
;                     else { *(f32x4*)(Xout + o) = v0; *(f32x4*)(Xout + o + 4) = v1; } }
;                 if (aux) { ss += __shfl_xor(ss, 16); ss += __shfl_xor(ss, 32); if (fq == 0) red[(ai * HALF + wr * 64 + m * 16 + fr) * 4 + wc] = ss; } } }
.LBB0_568:
	s_or_b64 exec, exec, s[16:17]
	s_waitcnt vmcnt(7)
	v_lshlrev_b32_e32 v34, 16, v78
	s_waitcnt lgkmcnt(0)
	v_and_b32_e32 v35, 0xffff0000, v78
	v_lshlrev_b32_e32 v36, 16, v79
	v_and_b32_e32 v37, 0xffff0000, v79
	v_lshlrev_b32_e32 v38, 16, v80
	v_and_b32_e32 v39, 0xffff0000, v80
	v_pk_add_f32 v[30:31], v[30:31], v[34:35]
	v_pk_add_f32 v[32:33], v[32:33], v[36:37]
	v_pk_add_f32 v[36:37], v[26:27], v[38:39]
	v_cvt_pk_bf16_f32 v26, v30, v31
	v_mul_f32_e32 v31, v31, v31
	v_fmac_f32_e32 v31, v30, v30
	v_mul_f32_e32 v30, v33, v33
	v_fmac_f32_e32 v30, v32, v32
	v_lshlrev_b32_e32 v40, 16, v81
	v_and_b32_e32 v41, 0xffff0000, v81
	v_add_f32_e32 v30, v31, v30
	v_mul_f32_e32 v31, v37, v37
	v_pk_add_f32 v[34:35], v[28:29], v[40:41]
	v_fmac_f32_e32 v31, v36, v36
	v_add_f32_e32 v30, v31, v30
	v_mul_f32_e32 v31, v35, v35
	v_fmac_f32_e32 v31, v34, v34
	v_cvt_pk_bf16_f32 v27, v32, v33
	v_add_f32_e32 v38, v31, v30
	s_waitcnt vmcnt(6)
	v_lshlrev_b32_e32 v30, 16, v74
	v_and_b32_e32 v31, 0xffff0000, v74
	v_lshlrev_b32_e32 v32, 16, v75
	v_and_b32_e32 v33, 0xffff0000, v75
	v_cvt_pk_bf16_f32 v28, v36, v37
	v_cvt_pk_bf16_f32 v29, v34, v35
	v_lshlrev_b32_e32 v34, 16, v76
	v_and_b32_e32 v35, 0xffff0000, v76
	v_pk_add_f32 v[24:25], v[24:25], v[32:33]
	v_pk_add_f32 v[22:23], v[22:23], v[30:31]
	v_pk_add_f32 v[32:33], v[18:19], v[34:35]
	v_mul_f32_e32 v18, v23, v23
	v_mul_f32_e32 v19, v25, v25
	v_fmac_f32_e32 v18, v22, v22
	v_fmac_f32_e32 v19, v24, v24
	v_lshlrev_b32_e32 v36, 16, v77
	v_and_b32_e32 v37, 0xffff0000, v77
	v_add_f32_e32 v18, v18, v19
	v_mul_f32_e32 v19, v33, v33
	v_pk_add_f32 v[30:31], v[20:21], v[36:37]
	v_fmac_f32_e32 v19, v32, v32
	v_add_f32_e32 v18, v19, v18
	v_mul_f32_e32 v19, v31, v31
	v_fmac_f32_e32 v19, v30, v30
	v_add_f32_e32 v18, v19, v18
	v_add_f32_e32 v21, v38, v18
	v_mov_b32_e32 v36, v21
	s_nop 1
	v_permlane16_swap_b32_e32 v21, v36
	v_lshl_add_u64 v[18:19], s[56:57], 0, v[92:93]
	v_lshl_add_u64 v[34:35], v[166:167], 1, v[18:19]
	global_store_dwordx4 v[34:35], v[26:29], off
	v_cvt_pk_bf16_f32 v20, v22, v23
	s_waitcnt lgkmcnt(0)
	v_add_f32_e32 v18, v21, v36
	v_mov_b32_e32 v19, v18
	s_nop 1
	v_permlane32_swap_b32_e32 v18, v19
	v_cvt_pk_bf16_f32 v21, v24, v25
	v_cvt_pk_bf16_f32 v22, v32, v33
	v_cvt_pk_bf16_f32 v23, v30, v31
	global_store_dwordx4 v[34:35], v[20:23], off offset:256
	s_and_saveexec_b64 s[16:17], s[40:41]
	s_cbranch_execz .LBB0_570
	s_waitcnt lgkmcnt(0)
	v_add_f32_e32 v18, v18, v19
	ds_write_b32 v193, v18 offset:2560
.LBB0_570:
	s_or_b64 exec, exec, s[16:17]
	s_waitcnt vmcnt(7)
	v_lshlrev_b32_e32 v18, 16, v70
	s_waitcnt lgkmcnt(0)
	v_and_b32_e32 v19, 0xffff0000, v70
	v_lshlrev_b32_e32 v20, 16, v71
	v_and_b32_e32 v21, 0xffff0000, v71
	v_lshlrev_b32_e32 v22, 16, v72
	v_and_b32_e32 v23, 0xffff0000, v72
	v_pk_add_f32 v[14:15], v[14:15], v[18:19]
	v_pk_add_f32 v[16:17], v[16:17], v[20:21]
	v_pk_add_f32 v[20:21], v[10:11], v[22:23]
	v_cvt_pk_bf16_f32 v10, v14, v15
	v_mul_f32_e32 v15, v15, v15
	v_fmac_f32_e32 v15, v14, v14
	v_mul_f32_e32 v14, v17, v17
	v_fmac_f32_e32 v14, v16, v16
	v_lshlrev_b32_e32 v24, 16, v73
	v_and_b32_e32 v25, 0xffff0000, v73
	v_add_f32_e32 v14, v15, v14
	v_mul_f32_e32 v15, v21, v21
	v_pk_add_f32 v[18:19], v[12:13], v[24:25]
	v_fmac_f32_e32 v15, v20, v20
	v_add_f32_e32 v14, v15, v14
	v_mul_f32_e32 v15, v19, v19
	v_fmac_f32_e32 v15, v18, v18
	v_cvt_pk_bf16_f32 v11, v16, v17
	v_add_f32_e32 v22, v15, v14
	s_waitcnt vmcnt(6)
	v_lshlrev_b32_e32 v14, 16, v66
	v_and_b32_e32 v15, 0xffff0000, v66
	v_lshlrev_b32_e32 v16, 16, v67
	v_and_b32_e32 v17, 0xffff0000, v67
	v_cvt_pk_bf16_f32 v12, v20, v21
	v_cvt_pk_bf16_f32 v13, v18, v19
	v_lshlrev_b32_e32 v18, 16, v68
	v_and_b32_e32 v19, 0xffff0000, v68
	v_pk_add_f32 v[8:9], v[8:9], v[16:17]
	v_pk_add_f32 v[6:7], v[6:7], v[14:15]
	v_pk_add_f32 v[16:17], v[2:3], v[18:19]
	v_mul_f32_e32 v2, v7, v7
	v_mul_f32_e32 v3, v9, v9
	v_fmac_f32_e32 v2, v6, v6
	v_fmac_f32_e32 v3, v8, v8
	v_lshlrev_b32_e32 v20, 16, v69
	v_and_b32_e32 v21, 0xffff0000, v69
	v_add_f32_e32 v2, v2, v3
	v_mul_f32_e32 v3, v17, v17
	v_pk_add_f32 v[14:15], v[4:5], v[20:21]
	v_fmac_f32_e32 v3, v16, v16
	v_add_f32_e32 v2, v3, v2
	v_mul_f32_e32 v3, v15, v15
	v_fmac_f32_e32 v3, v14, v14
	v_add_f32_e32 v2, v3, v2
	v_add_f32_e32 v5, v22, v2
	v_mov_b32_e32 v20, v5
	s_nop 1
	v_permlane16_swap_b32_e32 v5, v20
	v_lshl_add_u64 v[2:3], s[56:57], 0, v[90:91]
	v_lshl_add_u64 v[18:19], v[166:167], 1, v[2:3]
	global_store_dwordx4 v[18:19], v[10:13], off
	v_cvt_pk_bf16_f32 v4, v6, v7
	s_waitcnt lgkmcnt(0)
	v_add_f32_e32 v2, v5, v20
	v_mov_b32_e32 v3, v2
	s_nop 1
	v_permlane32_swap_b32_e32 v2, v3
	v_cvt_pk_bf16_f32 v5, v8, v9
	v_cvt_pk_bf16_f32 v6, v16, v17
	v_cvt_pk_bf16_f32 v7, v14, v15
	global_store_dwordx4 v[18:19], v[4:7], off offset:256
	s_and_saveexec_b64 s[16:17], s[40:41]
	s_cbranch_execz .LBB0_572
	s_waitcnt lgkmcnt(0)
	v_add_f32_e32 v2, v2, v3
	ds_write_b32 v193, v2 offset:2816

;     __device__ __forceinline__ void operator()(const f32x4 (&acc)[2][2][4][2], const Unit& u, int wr, int wc, int fr, int fq) const {
;     ...
;                 if (aux) { ss += __shfl_xor(ss, 16); ss += __shfl_xor(ss, 32); if (fq == 0) red[(ai * HALF + wr * 64 + m * 16 + fr) * 4 + wc] = ss; } } }
.LBB0_814:
	v_and_b32_e32 v115, 64, v211
	v_xor_b32_e32 v114, 16, v211
	v_add_u32_e32 v115, 64, v115
	v_cmp_lt_i32_e32 vcc, v114, v115
	v_xor_b32_e32 v116, 32, v211
	s_nop 0
	v_cndmask_b32_e32 v114, v211, v114, vcc
	v_lshlrev_b32_e32 v114, 2, v114
	v_mov_b32_e32 v114, v126
	s_nop 1
	v_permlane16_swap_b32_e32 v126, v114
	v_cmp_lt_i32_e32 vcc, v116, v115
	s_waitcnt lgkmcnt(0)
	v_add_f32_e32 v114, v126, v114
	v_cndmask_b32_e32 v115, v211, v116, vcc
	v_lshlrev_b32_e32 v115, 2, v115
	v_mov_b32_e32 v115, v114
	s_nop 1
	v_permlane32_swap_b32_e32 v114, v115
	s_and_saveexec_b64 s[24:25], s[38:39]
	s_cbranch_execz .LBB0_816
	s_waitcnt lgkmcnt(0)
	v_add_f32_e32 v114, v114, v115
	ds_write_b32 v201, v114

;     __device__ __forceinline__ void operator()(const f32x4 (&acc)[2][2][4][2], const Unit& u, int wr, int wc, int fr, int fq) const {
;     ...
;                 if (aux) { ss += __shfl_xor(ss, 16); ss += __shfl_xor(ss, 32); if (fq == 0) red[(ai * HALF + wr * 64 + m * 16 + fr) * 4 + wc] = ss; } } }
.LBB0_826:
	v_and_b32_e32 v99, 64, v211
	v_xor_b32_e32 v98, 16, v211
	v_add_u32_e32 v99, 64, v99
	v_cmp_lt_i32_e32 vcc, v98, v99
	v_xor_b32_e32 v100, 32, v211
	s_nop 0
	v_cndmask_b32_e32 v98, v211, v98, vcc
	v_lshlrev_b32_e32 v98, 2, v98
	v_mov_b32_e32 v98, v106
	s_nop 1
	v_permlane16_swap_b32_e32 v106, v98
	v_cmp_lt_i32_e32 vcc, v100, v99
	s_waitcnt lgkmcnt(0)
	v_add_f32_e32 v98, v106, v98
	v_cndmask_b32_e32 v99, v211, v100, vcc
	v_lshlrev_b32_e32 v99, 2, v99
	v_mov_b32_e32 v99, v98
	s_nop 1
	v_permlane32_swap_b32_e32 v98, v99
	s_and_saveexec_b64 s[24:25], s[38:39]
	s_cbranch_execz .LBB0_828
	s_waitcnt lgkmcnt(0)
	v_add_f32_e32 v98, v98, v99
	ds_write_b32 v201, v98 offset:256

;     __device__ __forceinline__ void operator()(const f32x4 (&acc)[2][2][4][2], const Unit& u, int wr, int wc, int fr, int fq) const {
;     ...
;                 if (aux) { ss += __shfl_xor(ss, 16); ss += __shfl_xor(ss, 32); if (fq == 0) red[(ai * HALF + wr * 64 + m * 16 + fr) * 4 + wc] = ss; } } }
.LBB0_838:
	v_and_b32_e32 v83, 64, v211
	v_xor_b32_e32 v82, 16, v211
	v_add_u32_e32 v83, 64, v83
	v_cmp_lt_i32_e32 vcc, v82, v83
	v_xor_b32_e32 v84, 32, v211
	s_nop 0
	v_cndmask_b32_e32 v82, v211, v82, vcc
	v_lshlrev_b32_e32 v82, 2, v82
	v_mov_b32_e32 v82, v90
	s_nop 1
	v_permlane16_swap_b32_e32 v90, v82
	v_cmp_lt_i32_e32 vcc, v84, v83
	s_waitcnt lgkmcnt(0)
	v_add_f32_e32 v82, v90, v82
	v_cndmask_b32_e32 v83, v211, v84, vcc
	v_lshlrev_b32_e32 v83, 2, v83
	v_mov_b32_e32 v83, v82
	s_nop 1
	v_permlane32_swap_b32_e32 v82, v83
	s_and_saveexec_b64 s[24:25], s[38:39]
	s_cbranch_execz .LBB0_840
	s_waitcnt lgkmcnt(0)
	v_add_f32_e32 v82, v82, v83
	ds_write_b32 v201, v82 offset:512

;     __device__ __forceinline__ void operator()(const f32x4 (&acc)[2][2][4][2], const Unit& u, int wr, int wc, int fr, int fq) const {
;     ...
;                 if (aux) { ss += __shfl_xor(ss, 16); ss += __shfl_xor(ss, 32); if (fq == 0) red[(ai * HALF + wr * 64 + m * 16 + fr) * 4 + wc] = ss; } } }
.LBB0_850:
	v_and_b32_e32 v67, 64, v211
	v_xor_b32_e32 v66, 16, v211
	v_add_u32_e32 v67, 64, v67
	v_cmp_lt_i32_e32 vcc, v66, v67
	v_xor_b32_e32 v68, 32, v211
	s_nop 0
	v_cndmask_b32_e32 v66, v211, v66, vcc
	v_lshlrev_b32_e32 v66, 2, v66
	v_mov_b32_e32 v66, v74
	s_nop 1
	v_permlane16_swap_b32_e32 v74, v66
	v_cmp_lt_i32_e32 vcc, v68, v67
	s_waitcnt lgkmcnt(0)
	v_add_f32_e32 v66, v74, v66
	v_cndmask_b32_e32 v67, v211, v68, vcc
	v_lshlrev_b32_e32 v67, 2, v67
	v_mov_b32_e32 v67, v66
	s_nop 1
	v_permlane32_swap_b32_e32 v66, v67
	s_and_saveexec_b64 s[24:25], s[38:39]
	s_cbranch_execz .LBB0_852
	s_waitcnt lgkmcnt(0)
	v_add_f32_e32 v66, v66, v67
	ds_write_b32 v201, v66 offset:768

;     __device__ __forceinline__ void operator()(const f32x4 (&acc)[2][2][4][2], const Unit& u, int wr, int wc, int fr, int fq) const {
;     ...
;                 if (aux) { ss += __shfl_xor(ss, 16); ss += __shfl_xor(ss, 32); if (fq == 0) red[(ai * HALF + wr * 64 + m * 16 + fr) * 4 + wc] = ss; } } }
.LBB0_862:
	v_and_b32_e32 v51, 64, v211
	v_xor_b32_e32 v50, 16, v211
	v_add_u32_e32 v51, 64, v51
	v_cmp_lt_i32_e32 vcc, v50, v51
	v_xor_b32_e32 v52, 32, v211
	s_nop 0
	v_cndmask_b32_e32 v50, v211, v50, vcc
	v_lshlrev_b32_e32 v50, 2, v50
	v_mov_b32_e32 v50, v58
	s_nop 1
	v_permlane16_swap_b32_e32 v58, v50
	v_cmp_lt_i32_e32 vcc, v52, v51
	s_waitcnt lgkmcnt(0)
	v_add_f32_e32 v50, v58, v50
	v_cndmask_b32_e32 v51, v211, v52, vcc
	v_lshlrev_b32_e32 v51, 2, v51
	v_mov_b32_e32 v51, v50
	s_nop 1
	v_permlane32_swap_b32_e32 v50, v51
	s_and_saveexec_b64 s[24:25], s[38:39]
	s_cbranch_execz .LBB0_864
	s_waitcnt lgkmcnt(0)
	v_add_f32_e32 v50, v50, v51
	ds_write_b32 v201, v50 offset:2048

;     __device__ __forceinline__ void operator()(const f32x4 (&acc)[2][2][4][2], const Unit& u, int wr, int wc, int fr, int fq) const {
;     ...
;                 if (aux) { ss += __shfl_xor(ss, 16); ss += __shfl_xor(ss, 32); if (fq == 0) red[(ai * HALF + wr * 64 + m * 16 + fr) * 4 + wc] = ss; } } }
.LBB0_874:
	v_and_b32_e32 v35, 64, v211
	v_xor_b32_e32 v34, 16, v211
	v_add_u32_e32 v35, 64, v35
	v_cmp_lt_i32_e32 vcc, v34, v35
	v_xor_b32_e32 v36, 32, v211
	s_nop 0
	v_cndmask_b32_e32 v34, v211, v34, vcc
	v_lshlrev_b32_e32 v34, 2, v34
	v_mov_b32_e32 v34, v42
	s_nop 1
	v_permlane16_swap_b32_e32 v42, v34
	v_cmp_lt_i32_e32 vcc, v36, v35
	s_waitcnt lgkmcnt(0)
	v_add_f32_e32 v34, v42, v34
	v_cndmask_b32_e32 v35, v211, v36, vcc
	v_lshlrev_b32_e32 v35, 2, v35
	v_mov_b32_e32 v35, v34
	s_nop 1
	v_permlane32_swap_b32_e32 v34, v35
	s_and_saveexec_b64 s[24:25], s[38:39]
	s_cbranch_execz .LBB0_876
	s_waitcnt lgkmcnt(0)
	v_add_f32_e32 v34, v34, v35
	ds_write_b32 v201, v34 offset:2304

;     __device__ __forceinline__ void operator()(const f32x4 (&acc)[2][2][4][2], const Unit& u, int wr, int wc, int fr, int fq) const {
;     ...
;                 if (aux) { ss += __shfl_xor(ss, 16); ss += __shfl_xor(ss, 32); if (fq == 0) red[(ai * HALF + wr * 64 + m * 16 + fr) * 4 + wc] = ss; } } }
.LBB0_886:
	v_and_b32_e32 v19, 64, v211
	v_xor_b32_e32 v18, 16, v211
	v_add_u32_e32 v19, 64, v19
	v_cmp_lt_i32_e32 vcc, v18, v19
	v_xor_b32_e32 v20, 32, v211
	s_nop 0
	v_cndmask_b32_e32 v18, v211, v18, vcc
	v_lshlrev_b32_e32 v18, 2, v18
	v_mov_b32_e32 v18, v26
	s_nop 1
	v_permlane16_swap_b32_e32 v26, v18
	v_cmp_lt_i32_e32 vcc, v20, v19
	s_waitcnt lgkmcnt(0)
	v_add_f32_e32 v18, v26, v18
	v_cndmask_b32_e32 v19, v211, v20, vcc
	v_lshlrev_b32_e32 v19, 2, v19
	v_mov_b32_e32 v19, v18
	s_nop 1
	v_permlane32_swap_b32_e32 v18, v19
	s_and_saveexec_b64 s[24:25], s[38:39]
	s_cbranch_execz .LBB0_888
	s_waitcnt lgkmcnt(0)
	v_add_f32_e32 v18, v18, v19
	ds_write_b32 v201, v18 offset:2560

;     __device__ __forceinline__ void operator()(const f32x4 (&acc)[2][2][4][2], const Unit& u, int wr, int wc, int fr, int fq) const {
;     ...
;                 if (aux) { ss += __shfl_xor(ss, 16); ss += __shfl_xor(ss, 32); if (fq == 0) red[(ai * HALF + wr * 64 + m * 16 + fr) * 4 + wc] = ss; } } }
.LBB0_899:
	v_and_b32_e32 v3, 64, v211
	v_xor_b32_e32 v2, 16, v211
	v_add_u32_e32 v3, 64, v3
	v_cmp_lt_i32_e32 vcc, v2, v3
	v_xor_b32_e32 v4, 32, v211
	s_nop 0
	v_cndmask_b32_e32 v2, v211, v2, vcc
	v_lshlrev_b32_e32 v2, 2, v2
	v_mov_b32_e32 v2, v10
	s_nop 1
	v_permlane16_swap_b32_e32 v10, v2
	v_cmp_lt_i32_e32 vcc, v4, v3
	s_waitcnt lgkmcnt(0)
	v_add_f32_e32 v2, v10, v2
	v_cndmask_b32_e32 v3, v211, v4, vcc
	v_lshlrev_b32_e32 v3, 2, v3
	v_mov_b32_e32 v3, v2
	s_nop 1
	v_permlane32_swap_b32_e32 v2, v3
	s_and_saveexec_b64 s[24:25], s[38:39]
	s_cbranch_execz .LBB0_901
	s_waitcnt lgkmcnt(0)
	v_add_f32_e32 v2, v2, v3
	ds_write_b32 v201, v2 offset:2816
